# S5 scan loops: per-step complex recurrence as 4 scalar f32 FMAs (depth 2) instead of packed add/mul/fma/mov chain; plus earlier epilogue load batching
# baseline (speedup 1.0000x reference)
; #define LAS __attribute__((address_space(3)))
; __device__ __forceinline__ unsigned pk2(float lo, float hi) { f32x2 v = {lo, hi}; bf16x2_t b = __builtin_convertvector(v, bf16x2_t); return __builtin_bit_cast(unsigned, b); }
; __device__ __forceinline__ void s5_unit(LAS unsigned char* lds, const Params& P, int l, int b, int g, const bf16_t* ub, bf16_t* y2) {
;     ...
;         for (int sc = 0; sc < 16; ++sc) {
;             const u32x4 uw = uw_n; const u32x2 uu_c = uu_n;
;             if (sc < 15) {
;                 if (kq < 2) uw_n = *(const u32x4*)(ub + (row0 + 16 * (sc + 1) + c15) * 256 + g * 16 + 8 * kq);
;                 if (0) uu_n = *(const u32x2*)(ub + (row0 + 16 * (sc + 1) + c15) * 256 + g * 16 + 4 * kq);
;             }
;             const bf16x8 uf = __builtin_bit_cast(bf16x8, uw);
; #pragma unroll
;             for (int nb = 0; nb < 8; ++nb) {
;                 const f32x4 d = __builtin_amdgcn_mfma_f32_16x16x32_bf16(uf, bfr[nb], (f32x4){0.f, 0.f, 0.f, 0.f}, 0, 0, 0);
;                 *(LAS f32x4*)(BUs + (16 * nb + c15) * 20 + 4 * kq) = d;
;             }
;             asm volatile("s_waitcnt lgkmcnt(0)" ::: "memory");
;             f32x4 bre4[4], bim4[4];
; #pragma unroll
;             for (int q = 0; q < 4; ++q) { bre4[q] = *(const LAS f32x4*)(BUs + lane * 20 + 4 * q); bim4[q] = *(const LAS f32x4*)(BUs + (64 + lane) * 20 + 4 * q); }
; #pragma unroll
;             for (int tt = 0; tt < 16; ++tt) {
;                 const float bre = bre4[tt >> 2][tt & 3], bim = bim4[tt >> 2][tt & 3];
;                 const float nxr = lbr * xr - lbi * xi + bre, nxi = lbr * xi + lbi * xr + bim; xr = nxr; xi = nxi;
;                 if (0) *(LAS unsigned*)(Xs + tt * 272 + lane * 4) = pk2(xr, xi);
;             }
.LBB0_608:
	s_or_b64 exec, exec, s[8:9]
	v_mfma_f32_16x16x32_bf16 v[108:111], v[76:79], v[12:15], 0
	s_nop 0
	s_nop 0
	s_add_u32 s12, s12, 0x2000
	s_nop 1
	v_mfma_f32_16x16x32_bf16 v[112:115], v[76:79], v[20:23], 0
	s_nop 0
	s_nop 0
	s_nop 0
	ds_write_b128 v104, v[108:111]
	s_nop 0
	v_mfma_f32_16x16x32_bf16 v[116:119], v[76:79], v[28:31], 0
	s_addc_u32 s13, s13, 0
	s_cmp_eq_u32 s12, 0x20000
	v_mfma_f32_16x16x32_bf16 v[120:123], v[76:79], v[36:39], 0
	ds_write_b128 v104, v[112:115] offset:1280
	s_nop 3
	ds_write_b128 v104, v[116:119] offset:2560
	s_nop 1
	ds_write_b128 v104, v[120:123] offset:3840
	v_mfma_f32_16x16x32_bf16 v[124:127], v[76:79], v[8:11], 0
	v_mfma_f32_16x16x32_bf16 v[108:111], v[76:79], v[16:19], 0
	v_mfma_f32_16x16x32_bf16 v[112:115], v[76:79], v[24:27], 0
	s_nop 5
	ds_write_b128 v104, v[124:127] offset:5120
	ds_write_b128 v104, v[108:111] offset:6400
	ds_write_b128 v104, v[112:115] offset:7680
	v_mfma_f32_16x16x32_bf16 v[76:79], v[76:79], v[32:35], 0
	s_nop 7
	ds_write_b128 v104, v[76:79] offset:8960
	s_waitcnt lgkmcnt(0)
	ds_read_b128 v[76:79], v105
	ds_read_b128 v[108:111], v105 offset:16
	ds_read_b128 v[112:115], v105 offset:32
	ds_read_b128 v[116:119], v105 offset:48
	ds_read_b128 v[120:123], v105 offset:5120
	ds_read_b128 v[124:127], v105 offset:5136
	ds_read_b128 v[128:131], v105 offset:5152
	ds_read_b128 v[132:135], v105 offset:5168
	s_waitcnt lgkmcnt(3)
	v_fma_f32 v136, -v84, v99, v76
	v_fma_f32 v137, v84, v98, v120
	v_fma_f32 v98, v2, v98, v136
	v_fma_f32 v99, v2, v99, v137
	v_fma_f32 v136, -v84, v99, v77
	v_fma_f32 v137, v84, v98, v121
	v_fma_f32 v98, v2, v98, v136
	v_fma_f32 v99, v2, v99, v137
	v_fma_f32 v136, -v84, v99, v78
	v_fma_f32 v137, v84, v98, v122
	v_fma_f32 v98, v2, v98, v136
	v_fma_f32 v99, v2, v99, v137
	v_fma_f32 v136, -v84, v99, v79
	v_fma_f32 v137, v84, v98, v123
	v_fma_f32 v98, v2, v98, v136
	v_fma_f32 v99, v2, v99, v137
	s_waitcnt lgkmcnt(2)
	v_fma_f32 v136, -v84, v99, v108
	v_fma_f32 v137, v84, v98, v124
	v_fma_f32 v98, v2, v98, v136
	v_fma_f32 v99, v2, v99, v137
	v_fma_f32 v136, -v84, v99, v109
	v_fma_f32 v137, v84, v98, v125
	v_fma_f32 v98, v2, v98, v136
	v_fma_f32 v99, v2, v99, v137
	v_fma_f32 v136, -v84, v99, v110
	v_fma_f32 v137, v84, v98, v126
	v_fma_f32 v98, v2, v98, v136
	v_fma_f32 v99, v2, v99, v137
	v_fma_f32 v136, -v84, v99, v111
	v_fma_f32 v137, v84, v98, v127
	v_fma_f32 v98, v2, v98, v136
	v_fma_f32 v99, v2, v99, v137
	s_waitcnt lgkmcnt(1)
	v_fma_f32 v136, -v84, v99, v112
	v_fma_f32 v137, v84, v98, v128
	v_fma_f32 v98, v2, v98, v136
	v_fma_f32 v99, v2, v99, v137
	v_fma_f32 v136, -v84, v99, v113
	v_fma_f32 v137, v84, v98, v129
	v_fma_f32 v98, v2, v98, v136
	v_fma_f32 v99, v2, v99, v137
	v_fma_f32 v136, -v84, v99, v114
	v_fma_f32 v137, v84, v98, v130
	v_fma_f32 v98, v2, v98, v136
	v_fma_f32 v99, v2, v99, v137
	v_fma_f32 v136, -v84, v99, v115
	v_fma_f32 v137, v84, v98, v131
	v_fma_f32 v98, v2, v98, v136
	v_fma_f32 v99, v2, v99, v137
	s_waitcnt lgkmcnt(0)
	v_fma_f32 v136, -v84, v99, v116
	v_fma_f32 v137, v84, v98, v132
	v_fma_f32 v98, v2, v98, v136
	v_fma_f32 v99, v2, v99, v137
	v_fma_f32 v136, -v84, v99, v117
	v_fma_f32 v137, v84, v98, v133
	v_fma_f32 v98, v2, v98, v136
	v_fma_f32 v99, v2, v99, v137
	v_fma_f32 v136, -v84, v99, v118
	v_fma_f32 v137, v84, v98, v134
	v_fma_f32 v98, v2, v98, v136
	v_fma_f32 v99, v2, v99, v137
	v_fma_f32 v136, -v84, v99, v119
	v_fma_f32 v137, v84, v98, v135
	v_fma_f32 v98, v2, v98, v136
	v_fma_f32 v99, v2, v99, v137
	s_waitcnt vmcnt(0)
	v_mov_b64_e32 v[78:79], v[74:75]
	v_mov_b64_e32 v[76:77], v[72:73]
	s_cbranch_scc1 .LBB0_611

; #define LAS __attribute__((address_space(3)))
; __device__ __forceinline__ unsigned pk2(float lo, float hi) { f32x2 v = {lo, hi}; bf16x2_t b = __builtin_convertvector(v, bf16x2_t); return __builtin_bit_cast(unsigned, b); }
; __device__ __forceinline__ void s5_unit(LAS unsigned char* lds, const Params& P, int l, int b, int g, const bf16_t* ub, bf16_t* y2) {
;     ...
;             const bf16x8 uf = __builtin_bit_cast(bf16x8, uw);
; #pragma unroll
;             for (int nb = 0; nb < 8; ++nb) {
;                 const f32x4 d = __builtin_amdgcn_mfma_f32_16x16x32_bf16(uf, bfr[nb], (f32x4){0.f, 0.f, 0.f, 0.f}, 0, 0, 0);
;                 *(LAS f32x4*)(BUs + (16 * nb + c15) * 20 + 4 * kq) = d;
;             }
;             asm volatile("s_waitcnt lgkmcnt(0)" ::: "memory");
;             f32x4 bre4[4], bim4[4];
; #pragma unroll
;             for (int q = 0; q < 4; ++q) { bre4[q] = *(const LAS f32x4*)(BUs + lane * 20 + 4 * q); bim4[q] = *(const LAS f32x4*)(BUs + (64 + lane) * 20 + 4 * q); }
; #pragma unroll
;             for (int tt = 0; tt < 16; ++tt) {
;                 const float bre = bre4[tt >> 2][tt & 3], bim = bim4[tt >> 2][tt & 3];
;                 const float nxr = lbr * xr - lbi * xi + bre, nxi = lbr * xi + lbi * xr + bim; xr = nxr; xi = nxi;
;                 if (1) *(LAS unsigned*)(Xs + tt * 272 + lane * 4) = pk2(xr, xi);
;             }
;             asm volatile("s_waitcnt lgkmcnt(0)" ::: "memory");
;             if (1) {
;                 f32x4 ya = (f32x4){0.f, 0.f, 0.f, 0.f};
; #pragma unroll
;                 for (int ks = 0; ks < 4; ++ks) { const bf16x8 a = *(const LAS bf16x8*)(Xs + c15 * 272 + (32 * ks + 8 * kq) * 2); ya = __builtin_amdgcn_mfma_f32_16x16x32_bf16(cfrg[ks], a, ya, 0, 0, 0); }
; { const long row = row0 + 16 * sc + c15; f32x4 o;
;                   const f32x4 uu = (f32x4){__uint_as_float(uu_c.x << 16), __uint_as_float(uu_c.x & 0xffff0000u), __uint_as_float(uu_c.y << 16), __uint_as_float(uu_c.y & 0xffff0000u)};
; #pragma unroll
;                   for (int e = 0; e < 4; ++e) { const float y = ya[e] + dh4[e] * uu[e]; const float z = 0.7978845608028654f * (y + 0.044715f * y * y * y);
;                       const float th = 1.f - 2.f * __builtin_amdgcn_rcpf(1.f + __builtin_amdgcn_exp2f(2.f * LOG2E * z)); o[e] = 0.5f * y * (1.f + th); }
;                   store4(y2 + row * 256 + g * 16 + 4 * kq, o); }
.LBB0_619:
	v_mfma_f32_16x16x32_bf16 v[86:89], v[72:75], v[12:15], 0
	s_add_u32 s14, s14, 16
	s_addc_u32 s15, s15, 0
	s_add_u32 s12, s12, 0x2000
	v_mfma_f32_16x16x32_bf16 v[90:93], v[72:75], v[20:23], 0
	s_addc_u32 s13, s13, 0
	s_nop 2
	ds_write_b128 v104, v[86:89]
	s_cmp_lg_u32 s12, 0x20000
	v_mfma_f32_16x16x32_bf16 v[94:97], v[72:75], v[28:31], 0
	v_mfma_f32_16x16x32_bf16 v[98:101], v[72:75], v[36:39], 0
	ds_write_b128 v104, v[90:93] offset:1280
	s_nop 5
	ds_write_b128 v104, v[94:97] offset:2560
	ds_write_b128 v104, v[98:101] offset:3840
	v_mfma_f32_16x16x32_bf16 v[106:109], v[72:75], v[8:11], 0
	v_mfma_f32_16x16x32_bf16 v[86:89], v[72:75], v[16:19], 0
	v_mfma_f32_16x16x32_bf16 v[90:93], v[72:75], v[24:27], 0
	s_nop 5
	ds_write_b128 v104, v[106:109] offset:5120
	ds_write_b128 v104, v[86:89] offset:6400
	ds_write_b128 v104, v[90:93] offset:7680
	v_mfma_f32_16x16x32_bf16 v[70:73], v[72:75], v[32:35], 0
	s_nop 0
	s_nop 0
	s_nop 1
	s_nop 1
	s_nop 0
	s_nop 0
	s_nop 1
	ds_write_b128 v104, v[70:73] offset:8960
	s_waitcnt lgkmcnt(0)
	ds_read_b128 v[70:73], v105
	ds_read_b128 v[86:89], v105 offset:16
	ds_read_b128 v[90:93], v105 offset:32
	ds_read_b128 v[94:97], v105 offset:48
	ds_read_b128 v[98:101], v105 offset:5120
	ds_read_b128 v[106:109], v105 offset:5136
	ds_read_b128 v[110:113], v105 offset:5152
	ds_read_b128 v[114:117], v105 offset:5168
	s_waitcnt lgkmcnt(3)
	v_add_u32_e32 v81, 0x2800, v68
	v_fma_f32 v74, -v84, v77, v70
	v_fma_f32 v75, v84, v76, v98
	v_fma_f32 v76, v2, v76, v74
	v_fma_f32 v77, v2, v77, v75
	v_cvt_pk_bf16_f32 v69, v76, v77
	v_fma_f32 v74, -v84, v77, v71
	v_fma_f32 v75, v84, v76, v99
	v_fma_f32 v76, v2, v76, v74
	v_fma_f32 v77, v2, v77, v75
	v_cvt_pk_bf16_f32 v80, v76, v77
	ds_write2_b32 v81, v69, v80 offset1:68
	v_fma_f32 v74, -v84, v77, v72
	v_fma_f32 v75, v84, v76, v100
	v_fma_f32 v76, v2, v76, v74
	v_fma_f32 v77, v2, v77, v75
	v_cvt_pk_bf16_f32 v69, v76, v77
	v_fma_f32 v74, -v84, v77, v73
	v_fma_f32 v75, v84, v76, v101
	v_fma_f32 v76, v2, v76, v74
	v_fma_f32 v77, v2, v77, v75
	v_cvt_pk_bf16_f32 v80, v76, v77
	ds_write2_b32 v81, v69, v80 offset0:136 offset1:204
	s_waitcnt lgkmcnt(4)
	v_add_u32_e32 v81, 0x2c40, v68
	v_fma_f32 v74, -v84, v77, v86
	v_fma_f32 v75, v84, v76, v106
	v_fma_f32 v76, v2, v76, v74
	v_fma_f32 v77, v2, v77, v75
	v_cvt_pk_bf16_f32 v69, v76, v77
	v_fma_f32 v74, -v84, v77, v87
	v_fma_f32 v75, v84, v76, v107
	v_fma_f32 v76, v2, v76, v74
	v_fma_f32 v77, v2, v77, v75
	v_cvt_pk_bf16_f32 v80, v76, v77
	ds_write2_b32 v81, v69, v80 offset1:68
	v_fma_f32 v74, -v84, v77, v88
	v_fma_f32 v75, v84, v76, v108
	v_fma_f32 v76, v2, v76, v74
	v_fma_f32 v77, v2, v77, v75
	v_cvt_pk_bf16_f32 v69, v76, v77
	v_fma_f32 v74, -v84, v77, v89
	v_fma_f32 v75, v84, v76, v109
	v_fma_f32 v76, v2, v76, v74
	v_fma_f32 v77, v2, v77, v75
	v_cvt_pk_bf16_f32 v80, v76, v77
	ds_write2_b32 v81, v69, v80 offset0:136 offset1:204
	s_waitcnt lgkmcnt(5)
	v_add_u32_e32 v81, 0x3080, v68
	v_fma_f32 v74, -v84, v77, v90
	v_fma_f32 v75, v84, v76, v110
	v_fma_f32 v76, v2, v76, v74
	v_fma_f32 v77, v2, v77, v75
	v_cvt_pk_bf16_f32 v69, v76, v77
	v_fma_f32 v74, -v84, v77, v91
	v_fma_f32 v75, v84, v76, v111
	v_fma_f32 v76, v2, v76, v74
	v_fma_f32 v77, v2, v77, v75
	v_cvt_pk_bf16_f32 v80, v76, v77
	ds_write2_b32 v81, v69, v80 offset1:68
	v_fma_f32 v74, -v84, v77, v92
	v_fma_f32 v75, v84, v76, v112
	v_fma_f32 v76, v2, v76, v74
	v_fma_f32 v77, v2, v77, v75
	v_cvt_pk_bf16_f32 v69, v76, v77
	v_fma_f32 v74, -v84, v77, v93
	v_fma_f32 v75, v84, v76, v113
	v_fma_f32 v76, v2, v76, v74
	v_fma_f32 v77, v2, v77, v75
	v_cvt_pk_bf16_f32 v80, v76, v77
	ds_write2_b32 v81, v69, v80 offset0:136 offset1:204
	s_waitcnt lgkmcnt(6)
	v_add_u32_e32 v81, 0x34c0, v68
	v_fma_f32 v74, -v84, v77, v94
	v_fma_f32 v75, v84, v76, v114
	v_fma_f32 v76, v2, v76, v74
	v_fma_f32 v77, v2, v77, v75
	v_cvt_pk_bf16_f32 v69, v76, v77
	v_fma_f32 v74, -v84, v77, v95
	v_fma_f32 v75, v84, v76, v115
	v_fma_f32 v76, v2, v76, v74
	v_fma_f32 v77, v2, v77, v75
	v_cvt_pk_bf16_f32 v80, v76, v77
	ds_write2_b32 v81, v69, v80 offset1:68
	v_fma_f32 v74, -v84, v77, v96
	v_fma_f32 v75, v84, v76, v116
	v_fma_f32 v76, v2, v76, v74
	v_fma_f32 v77, v2, v77, v75
	v_cvt_pk_bf16_f32 v69, v76, v77
	v_fma_f32 v74, -v84, v77, v97
	v_fma_f32 v75, v84, v76, v117
	v_fma_f32 v76, v2, v76, v74
	v_fma_f32 v77, v2, v77, v75
	v_cvt_pk_bf16_f32 v80, v76, v77
	ds_write2_b32 v81, v69, v80 offset0:136 offset1:204
	v_lshlrev_b32_e32 v74, 16, v78
	s_waitcnt lgkmcnt(0)
	ds_read_b128 v[70:73], v0 offset:10240
	ds_read_b128 v[86:89], v0 offset:10304
	s_waitcnt lgkmcnt(1)
	v_mfma_f32_16x16x32_bf16 v[70:73], v[52:55], v[70:73], 0
	v_and_b32_e32 v75, 0xffff0000, v78
	v_lshlrev_b32_e32 v78, 16, v79
	v_and_b32_e32 v79, 0xffff0000, v79
	s_waitcnt lgkmcnt(0)
	v_mfma_f32_16x16x32_bf16 v[70:73], v[48:51], v[86:89], v[70:73]
	ds_read_b128 v[86:89], v0 offset:10368
	ds_read_b128 v[90:93], v0 offset:10432
	s_waitcnt lgkmcnt(1)
	v_mfma_f32_16x16x32_bf16 v[70:73], v[44:47], v[86:89], v[70:73]
	s_waitcnt lgkmcnt(0)
	v_mfma_f32_16x16x32_bf16 v[70:73], v[40:43], v[90:93], v[70:73]
	s_nop 7
	v_pk_fma_f32 v[70:71], v[4:5], v[74:75], v[70:71]
	v_pk_fma_f32 v[72:73], v[6:7], v[78:79], v[72:73]
	v_mul_f32_e32 v69, 0x3d372713, v70
	v_mul_f32_e32 v69, v70, v69
	v_mul_f32_e32 v74, 0x3d372713, v71
	v_fma_f32 v69, v70, v69, v70
	v_mul_f32_e32 v74, v71, v74
	v_mul_f32_e32 v69, 0x3f4c422a, v69
	v_fma_f32 v74, v71, v74, v71
	v_mul_f32_e32 v69, 0x4038aa3b, v69
	v_mul_f32_e32 v74, 0x3f4c422a, v74
	v_exp_f32_e32 v69, v69
	v_mul_f32_e32 v74, 0x4038aa3b, v74
	v_exp_f32_e32 v75, v74
	v_mul_f32_e32 v78, 0x3d372713, v73
	v_add_f32_e32 v69, 1.0, v69
	v_rcp_f32_e32 v74, v69
	v_add_f32_e32 v69, 1.0, v75
	v_rcp_f32_e32 v75, v69
	v_mul_f32_e32 v69, 0x3d372713, v72
	v_mul_f32_e32 v69, v72, v69
	v_fma_f32 v69, v72, v69, v72
	v_mul_f32_e32 v78, v73, v78
	v_mul_f32_e32 v69, 0x3f4c422a, v69
	v_fma_f32 v78, v73, v78, v73
	v_mul_f32_e32 v69, 0x4038aa3b, v69
	v_mul_f32_e32 v78, 0x3f4c422a, v78
	v_exp_f32_e32 v69, v69
	v_mul_f32_e32 v78, 0x4038aa3b, v78
	v_exp_f32_e32 v79, v78
	v_pk_fma_f32 v[74:75], v[74:75], 2.0, 1.0 op_sel_hi:[1,0,0] neg_lo:[1,0,0] neg_hi:[1,0,0]
	v_add_f32_e32 v69, 1.0, v69
	v_rcp_f32_e32 v78, v69
	v_add_f32_e32 v69, 1.0, v79
	v_rcp_f32_e32 v79, v69
	v_pk_mul_f32 v[70:71], v[70:71], 0.5 op_sel_hi:[1,0]
	v_pk_add_f32 v[74:75], v[74:75], 1.0 op_sel_hi:[1,0]
	v_pk_mul_f32 v[72:73], v[72:73], 0.5 op_sel_hi:[1,0]
	v_pk_mul_f32 v[70:71], v[70:71], v[74:75]
	v_pk_fma_f32 v[74:75], v[78:79], 2.0, 1.0 op_sel_hi:[1,0,0] neg_lo:[1,0,0] neg_hi:[1,0,0]
	v_cvt_pk_bf16_f32 v70, v70, v71
	v_pk_add_f32 v[74:75], v[74:75], 1.0 op_sel_hi:[1,0]
	s_waitcnt vmcnt(0)
	v_mov_b64_e32 v[78:79], v[66:67]
	v_pk_mul_f32 v[72:73], v[72:73], v[74:75]
	v_or_b32_e32 v75, s17, v83
	v_or_b32_e32 v74, s16, v82
	v_lshlrev_b64 v[74:75], 9, v[74:75]
	v_lshl_add_u64 v[74:75], v[60:61], 0, v[74:75]
	v_cvt_pk_bf16_f32 v71, v72, v73
	global_store_dwordx2 v[74:75], v[70:71], off
	s_waitcnt lgkmcnt(0)
	v_mov_b64_e32 v[74:75], v[58:59]
	v_mov_b64_e32 v[72:73], v[56:57]
	s_cbranch_scc0 .LBB0_564
